# K-prep hook (mixer A k tile): the 8 per-lane qk-norm gains are loaded once per unit instead of one dependent load + vmcnt(0) per element per row group
# speedup vs baseline: 1.0064x; 1.0003x over previous
; #define ARG_WS() ((unsigned char*)karg<128>())
; __device__ __forceinline__ v4u prep_compute(const v4u rw, const f32x4 (&tb)[4], int type, int sub, const float* qkg) {
;     ...
;     for (int i = 0; i < 8; ++i) v[i] = isA ? (v[i] * rn) * gp[i] : v[i];
;     __device__ __forceinline__ void done(const pg8::Unit& u) const {
;         const int colt = u.pn * 256;
;         if (even ? !(colt == 512 || colt == 1280 || colt == 1536) : (colt != 1024)) return;
;         asm volatile("s_waitcnt vmcnt(0)" ::: "memory");
;         __builtin_amdgcn_s_barrier();
;         asm volatile("" ::: "memory");
;         int tid_ = threadIdx.x; asm volatile("" : "+v"(tid_));
;         const int sub = tid_ & 7, gidx = tid_ >> 3;
;         unsigned char* const ws = ARG_WS(); bf16* const QKV = (bf16*)(ws + WS_QKV); const f32x2* const ropeT = (const f32x2*)(ws + WS_ROPE); const f32x2* const axT = (const f32x2*)(ws + WS_AX);
;         const float* const qkg = ARG_IN(4) + (size_t)l2 * 128;
;         const int PITCH = nN * 256;
;         const int nh = (even && colt == 512) ? 2 : 4;
;         const int nit = (256 * nh) / 64;
;         constexpr int U = 4;
; #pragma unroll 1
;         for (int it = 0; it < nit; it += U) {
;             bf16* p[U]; int type[U]; v4u raw[U]; f32x4 tb[U][4];
; #pragma unroll
;             for (int k = 0; k < U; ++k) {
;                 const int hvi = (it + k) * 64 + gidx, rl = (nh == 2) ? (hvi >> 1) : (hvi >> 2), col = colt + 64 * ((nh == 2) ? (hvi & 1) : (hvi & 3)), row = u.pm * 256 + rl;
;                 const int ty = (even && colt == 512) ? 1 : 3;
;                 type[k] = ty; p[k] = QKV + (size_t)row * PITCH + col + 8 * sub;
;                 raw[k] = *(const v4u*)p[k];
;                 const int t = row < MP ? (row & 8191) : (row & 4095);
;                 const int aidx = (sub < 4) ? (t >> 6) : (t & 63);
;                 const f32x2* cs = (ty < 2) ? axT + aidx * 16 + 8 * (sub & 1) : ropeT + t * 8;
;                 tb[k][0] = *(const f32x4*)(cs); tb[k][1] = *(const f32x4*)(cs + 2); tb[k][2] = *(const f32x4*)(cs + 4); tb[k][3] = *(const f32x4*)(cs + 6);
.LBB0_133:
	s_and_b64 vcc, exec, s[8:9]
	s_cbranch_vccz .LBB0_221
	v_readlane_b32 s2, v255, 9
	v_mov_b32_e32 v6, v240
	v_readlane_b32 s3, v255, 10
	s_waitcnt vmcnt(0)
	s_barrier
	s_load_dwordx2 s[92:93], s[2:3], 0x80
	s_waitcnt lgkmcnt(0)
	s_load_dwordx2 s[2:3], s[2:3], 32
	s_waitcnt lgkmcnt(0)
	s_add_u32 s10, s2, s33
	s_addc_u32 s11, s3, 0
	s_cmp_eq_u32 s6, 2
	s_cselect_b64 s[2:3], -1, 0
	s_and_b64 s[6:7], s[74:75], s[2:3]
	s_xor_b64 s[94:95], s[6:7], -1
	s_and_b64 s[2:3], s[6:7], exec
	v_ashrrev_i32_e32 v103, 3, v6
	s_cselect_b32 s8, 1, 3
	v_and_b32_e32 v2, s8, v103
	v_and_b32_e32 v102, 7, v6
	v_lshl_or_b32 v2, v2, 6, s15
	v_mov_b32_e32 v3, v0
	v_lshl_add_u64 v[2:3], v[2:3], 1, s[92:93]
	v_lshlrev_b32_e32 v4, 4, v102
	v_mov_b32_e32 v5, v0
	v_lshl_add_u64 v[2:3], v[2:3], 0, v[4:5]
	s_mov_b64 s[8:9], 0x19a00000
	v_lshl_add_u64 v[82:83], v[2:3], 0, s[8:9]
	v_lshlrev_b32_e32 v2, 6, v6
	v_and_b32_e32 v2, 64, v2
	v_mov_b32_e32 v3, v0
	v_lshl_add_u64 v[2:3], s[92:93], 0, v[2:3]
	s_mov_b64 s[20:21], 0x80000
	v_lshl_add_u64 v[84:85], v[2:3], 0, s[20:21]
	v_lshlrev_b32_e32 v2, 5, v102
	v_mov_b32_e32 v3, v0
	s_cselect_b32 s2, 8, 16
	s_cselect_b32 s3, 1, 2
	v_cmp_gt_u32_e64 s[8:9], 4, v102
	v_lshl_add_u64 v[86:87], s[10:11], 0, v[2:3]
	v_cmp_gt_u32_e64 s[96:97], 2, v102
	s_cmp_eq_u64 s[6:7], 0
	s_cbranch_scc1 .Lmy_k3
	global_load_dword v112, v[86:87], off offset:256
	global_load_dword v113, v[86:87], off offset:260
	global_load_dword v114, v[86:87], off offset:264
	global_load_dword v115, v[86:87], off offset:268
	global_load_dword v116, v[86:87], off offset:272
	global_load_dword v117, v[86:87], off offset:276
	global_load_dword v118, v[86:87], off offset:280
	global_load_dword v119, v[86:87], off offset:284
	s_mov_b32 s15, 0
	s_branch .LBB0_137
.LBB0_135:
	v_mul_f32_e32 v19, v20, v19
	s_mov_b32 s20, 2
	s_or_b64 s[10:11], s[96:97], exec
	v_mul_f32_e32 v19, v19, v119

; __device__ __forceinline__ v4u prep_compute(const v4u rw, const f32x4 (&tb)[4], int type, int sub, const float* qkg) {
;     ...
;     const float* gp = qkg + (type & 1) * 64 + 8 * sub;
; #pragma unroll
;     for (int i = 0; i < 8; ++i) v[i] = isA ? (v[i] * rn) * gp[i] : v[i];
.LBB0_161:
	v_mul_f32_e32 v79, v80, v79
	s_mov_b32 s20, 2
	s_or_b64 s[36:37], s[96:97], exec
	v_mul_f32_e32 v79, v79, v119
	s_branch .LBB0_170
.LBB0_162:
	v_mul_f32_e32 v100, v80, v100
	v_mul_f32_e32 v100, v100, v112
	s_and_b64 vcc, exec, s[10:11]
	s_cbranch_vccnz .LBB0_155
.LBB0_163:
	v_mul_f32_e32 v98, v80, v98
	v_mul_f32_e32 v98, v98, v113
	s_and_b64 vcc, exec, s[10:11]
	s_cbranch_vccnz .LBB0_156
.LBB0_164:
	v_mul_f32_e32 v101, v80, v101
	v_mul_f32_e32 v101, v101, v114
	s_and_b64 vcc, exec, s[10:11]
	s_cbranch_vccnz .LBB0_157
.LBB0_165:
	v_mul_f32_e32 v99, v80, v99
	v_mul_f32_e32 v99, v99, v115
	s_and_b64 vcc, exec, s[10:11]
	s_cbranch_vccnz .LBB0_158
.LBB0_166:
	v_mul_f32_e32 v96, v80, v96
	v_mul_f32_e32 v96, v96, v116
	s_and_b64 vcc, exec, s[10:11]
	s_cbranch_vccnz .LBB0_159
.LBB0_167:
	v_mul_f32_e32 v78, v80, v78
	v_mul_f32_e32 v78, v78, v117
	s_and_b64 vcc, exec, s[10:11]
	s_cbranch_vccnz .LBB0_160
.LBB0_168:
	v_mul_f32_e32 v97, v80, v97
	v_mul_f32_e32 v97, v97, v118
	s_and_b64 vcc, exec, s[10:11]
	s_mov_b32 s20, 1
	s_cbranch_vccz .LBB0_161

; __device__ __forceinline__ v4u prep_compute(const v4u rw, const f32x4 (&tb)[4], int type, int sub, const float* qkg) {
;     ...
;     const float* gp = qkg + (type & 1) * 64 + 8 * sub;
; #pragma unroll
;     for (int i = 0; i < 8; ++i) v[i] = isA ? (v[i] * rn) * gp[i] : v[i];
.LBB0_178:
	v_mul_f32_e32 v59, v60, v59
	s_mov_b32 s20, 2
	s_or_b64 s[36:37], s[96:97], exec
	v_mul_f32_e32 v59, v59, v119
	s_branch .LBB0_187
.LBB0_179:
	v_mul_f32_e32 v66, v60, v66
	v_mul_f32_e32 v66, v66, v112
	s_and_b64 vcc, exec, s[10:11]
	s_cbranch_vccnz .LBB0_172
.LBB0_180:
	v_mul_f32_e32 v64, v60, v64
	v_mul_f32_e32 v64, v64, v113
	s_and_b64 vcc, exec, s[10:11]
	s_cbranch_vccnz .LBB0_173
.LBB0_181:
	v_mul_f32_e32 v67, v60, v67
	v_mul_f32_e32 v67, v67, v114
	s_and_b64 vcc, exec, s[10:11]
	s_cbranch_vccnz .LBB0_174
.LBB0_182:
	v_mul_f32_e32 v65, v60, v65
	v_mul_f32_e32 v65, v65, v115
	s_and_b64 vcc, exec, s[10:11]
	s_cbranch_vccnz .LBB0_175
.LBB0_183:
	v_mul_f32_e32 v62, v60, v62
	v_mul_f32_e32 v62, v62, v116
	s_and_b64 vcc, exec, s[10:11]
	s_cbranch_vccnz .LBB0_176
.LBB0_184:
	v_mul_f32_e32 v58, v60, v58
	v_mul_f32_e32 v58, v58, v117
	s_and_b64 vcc, exec, s[10:11]
	s_cbranch_vccnz .LBB0_177
.LBB0_185:
	v_mul_f32_e32 v63, v60, v63
	v_mul_f32_e32 v63, v63, v118
	s_and_b64 vcc, exec, s[10:11]
	s_mov_b32 s20, 1
	s_cbranch_vccz .LBB0_178

; __device__ __forceinline__ v4u prep_compute(const v4u rw, const f32x4 (&tb)[4], int type, int sub, const float* qkg) {
;     ...
;     const float* gp = qkg + (type & 1) * 64 + 8 * sub;
; #pragma unroll
;     for (int i = 0; i < 8; ++i) v[i] = isA ? (v[i] * rn) * gp[i] : v[i];
.LBB0_195:
	v_mul_f32_e32 v39, v40, v39
	s_mov_b32 s20, 2
	s_or_b64 s[36:37], s[96:97], exec
	v_mul_f32_e32 v39, v39, v119
	s_branch .LBB0_204
.LBB0_196:
	v_mul_f32_e32 v46, v40, v46
	v_mul_f32_e32 v46, v46, v112
	s_and_b64 vcc, exec, s[10:11]
	s_cbranch_vccnz .LBB0_189
.LBB0_197:
	v_mul_f32_e32 v44, v40, v44
	v_mul_f32_e32 v44, v44, v113
	s_and_b64 vcc, exec, s[10:11]
	s_cbranch_vccnz .LBB0_190
.LBB0_198:
	v_mul_f32_e32 v47, v40, v47
	v_mul_f32_e32 v47, v47, v114
	s_and_b64 vcc, exec, s[10:11]
	s_cbranch_vccnz .LBB0_191
.LBB0_199:
	v_mul_f32_e32 v45, v40, v45
	v_mul_f32_e32 v45, v45, v115
	s_and_b64 vcc, exec, s[10:11]
	s_cbranch_vccnz .LBB0_192
.LBB0_200:
	v_mul_f32_e32 v42, v40, v42
	v_mul_f32_e32 v42, v42, v116
	s_and_b64 vcc, exec, s[10:11]
	s_cbranch_vccnz .LBB0_193
.LBB0_201:
	v_mul_f32_e32 v38, v40, v38
	v_mul_f32_e32 v38, v38, v117
	s_and_b64 vcc, exec, s[10:11]
	s_cbranch_vccnz .LBB0_194
.LBB0_202:
	v_mul_f32_e32 v43, v40, v43
	v_mul_f32_e32 v43, v43, v118
	s_and_b64 vcc, exec, s[10:11]
	s_mov_b32 s20, 1
	s_cbranch_vccz .LBB0_195

; __device__ __forceinline__ v4u prep_compute(const v4u rw, const f32x4 (&tb)[4], int type, int sub, const float* qkg) {
;     ...
;     const float* gp = qkg + (type & 1) * 64 + 8 * sub;
; #pragma unroll
;     for (int i = 0; i < 8; ++i) v[i] = isA ? (v[i] * rn) * gp[i] : v[i];
.LBB0_212:
	v_mul_f32_e32 v26, v20, v26
	v_mul_f32_e32 v26, v26, v112
	s_and_b64 vcc, exec, s[10:11]
	s_cbranch_vccnz .LBB0_206
.LBB0_213:
	v_mul_f32_e32 v24, v20, v24
	v_mul_f32_e32 v24, v24, v113
	s_and_b64 vcc, exec, s[10:11]
	s_cbranch_vccnz .LBB0_207
.LBB0_214:
	v_mul_f32_e32 v27, v20, v27
	v_mul_f32_e32 v27, v27, v114
	s_and_b64 vcc, exec, s[10:11]
	s_cbranch_vccnz .LBB0_208
.LBB0_215:
	v_mul_f32_e32 v25, v20, v25
	v_mul_f32_e32 v25, v25, v115
	s_and_b64 vcc, exec, s[10:11]
	s_cbranch_vccnz .LBB0_209
.LBB0_216:
	v_mul_f32_e32 v22, v20, v22
	v_mul_f32_e32 v22, v22, v116
	s_and_b64 vcc, exec, s[10:11]
	s_cbranch_vccnz .LBB0_210
.LBB0_217:
	v_mul_f32_e32 v18, v20, v18
	v_mul_f32_e32 v18, v18, v117
	s_and_b64 vcc, exec, s[10:11]
	s_cbranch_vccnz .LBB0_211
.LBB0_218:
	v_mul_f32_e32 v23, v20, v23
	v_mul_f32_e32 v23, v23, v118
	s_and_b64 vcc, exec, s[10:11]
	s_mov_b32 s20, 1
	s_cbranch_vccz .LBB0_135
